# EpiMix A-head qk-norm: all four gamma vectors loaded once per tile and kept in VGPRs (v246-251,v200-201 + dead block-1 accumulators v120-127); 28 serialized load round trips per tile removed
# speedup vs baseline: 1.0071x; 1.0019x over previous
; __device__ __forceinline__ unsigned cvt_pk_bf16(float lo, float hi) { const f32x2 v = {lo, hi}; const bf16x2_t b = __builtin_convertvector(v, bf16x2_t); return __builtin_bit_cast(unsigned, b); }
;     __device__ __forceinline__ void operator()(const f32x4 (&acc)[2][2][4][2], const Unit& u, int wr, int wc, int fr, int fq) const {
;     ...
;             const int slot = u.pn * 4 + wc; const bool isq = slot < 6;
;             const float* g = isq ? gq : gk;
;             bf16_t* dst = isq ? (bf16_t*)(mx + MX_QA) + (size_t)slot * R * 64 : (bf16_t*)(mx + MX_KA) + (size_t)(slot - 6) * R * 64;
;     ...
;                     for (int bj = 0; bj < 2; ++bj) {
;                         u32x4 w;
; #pragma unroll
;                         for (int n = 0; n < 2; ++n) {
;                             f32x4 x = v[bj][n] * rstd * *(const f32x4*)(g + 32 * bj + 8 * fqo + 4 * n);
;                             if (latent) {
;                                 const float a0 = pos[bj] * fr0[n], a1 = pos[bj] * fr1[n];
;                                 const float c0 = __builtin_amdgcn_cosf(a0), s0 = __builtin_amdgcn_sinf(a0), c1 = __builtin_amdgcn_cosf(a1), s1 = __builtin_amdgcn_sinf(a1);
;                                 x = (f32x4){x[0] * c0 - x[1] * s0, x[1] * c0 + x[0] * s0, x[2] * c1 - x[3] * s1, x[3] * c1 + x[2] * s1};
;                             }
;                             if (n == 0) { w.x = cvt_pk_bf16(x[0], x[1]); w.y = cvt_pk_bf16(x[2], x[3]); } else { w.z = cvt_pk_bf16(x[0], x[1]); w.w = cvt_pk_bf16(x[2], x[3]); }
;                         }
;                         *(u32x4*)(dst + (size_t)row * 64 + 32 * bj + 8 * fq) = w;
.LBB0_457:
	s_add_i32 s18, s15, -6
	s_ashr_i32 s19, s15, 31
	s_and_b64 s[0:1], s[0:1], exec
	s_cselect_b32 s0, s15, s18
	s_cselect_b32 s1, s19, 0
	s_cselect_b32 s15, 0, 0x18c0000
	s_add_u32 s15, s90, s15
	s_mul_i32 s1, s1, 0x420000
	s_mul_hi_u32 s19, s0, 0x420000
	s_addc_u32 s18, s91, 0
	s_add_i32 s19, s19, s1
	s_mul_i32 s0, s0, 0x420000
	v_cvt_pk_bf16_f32 v158, v142, v143
	s_add_u32 s0, s15, s0
	v_lshlrev_b32_e32 v142, 3, v236
	s_addc_u32 s1, s18, s19
	v_ashrrev_i32_e32 v143, 31, v142
	v_ashrrev_i32_e32 v141, 31, v140
	v_cvt_pk_bf16_f32 v159, v144, v145
	v_lshl_add_u64 v[142:143], v[142:143], 1, s[0:1]
	v_lshlrev_b64 v[144:145], 7, v[140:141]
	v_lshl_add_u64 v[156:157], v[142:143], 0, v[144:145]
	v_cvt_pk_bf16_f32 v160, v148, v149
	v_cvt_pk_bf16_f32 v161, v154, v155
	global_store_dwordx4 v[156:157], v[158:161], off
	v_mul_f32_e32 v148, v110, v146
	v_mul_f32_e32 v149, v111, v147
	global_load_dwordx4 v[144:147], v[152:153], off offset:128
	v_and_b32_e32 v180, 63, v235
	v_cvt_f32_ubyte0_e32 v166, v180
	v_mul_f32_e32 v154, v108, v150
	v_mul_f32_e32 v155, v109, v151
	v_mul_f32_e32 v141, v194, v166
	s_and_b64 vcc, exec, s[36:37]
	s_waitcnt vmcnt(0)
	v_mov_b32_e32 v120, v144
	v_mov_b32_e32 v121, v145
	v_mov_b32_e32 v122, v146
	v_mov_b32_e32 v123, v147
	v_mul_f32_e32 v158, v154, v144
	v_mul_f32_e32 v159, v155, v145
	v_mul_f32_e32 v145, v237, v166
	v_mul_f32_e32 v160, v148, v146
	v_mul_f32_e32 v161, v149, v147
	v_cos_f32_e32 v146, v141
	v_sin_f32_e32 v148, v141
	v_cos_f32_e32 v144, v145
	v_sin_f32_e32 v145, v145
	s_cbranch_vccnz .LBB0_459
	v_mul_f32_e32 v162, v148, v159
	v_mul_f32_e32 v163, v148, v158
	v_mul_f32_e32 v154, v146, v158
	v_mul_f32_e32 v155, v146, v159
	v_fma_f32 v158, v146, v158, v162
	v_fma_f32 v159, v146, v159, v163
	v_mul_f32_e32 v158, v145, v161
	v_fma_f32 v164, v144, v160, -v158
	v_fma_f32 v165, v145, v161, -v158
	v_mov_b32_e32 v168, v145
	v_mov_b32_e32 v169, v144
	v_mul_f32_e32 v158, v144, v161
	v_fma_f32 v168, v168, v160, v158
	v_fma_f32 v169, v169, v161, v158
	v_sub_f32_e32 v158, v154, v162
	v_mov_b32_e32 v160, v164
	v_mov_b32_e32 v161, v168
.LBB0_459:
	v_mov_b32_e32 v154, v150
	v_mov_b32_e32 v155, v150
	v_mul_f32_e32 v162, v104, v150
	v_mul_f32_e32 v163, v105, v151
	global_load_dwordx4 v[150:153], v[152:153], off offset:144
	v_mul_f32_e32 v154, v106, v154
	v_mul_f32_e32 v155, v107, v155
	v_mul_f32_e32 v141, v238, v166
	v_mul_f32_e32 v147, v239, v166
	s_and_b64 vcc, exec, s[36:37]
	s_waitcnt vmcnt(0)
	v_mov_b32_e32 v124, v150
	v_mov_b32_e32 v125, v151
	v_mov_b32_e32 v126, v152
	v_mov_b32_e32 v127, v153
	v_mul_f32_e32 v164, v154, v152
	v_mul_f32_e32 v165, v155, v153
	v_mul_f32_e32 v162, v162, v150
	v_mul_f32_e32 v163, v163, v151
	v_cos_f32_e32 v152, v141
	v_sin_f32_e32 v154, v141
	v_cos_f32_e32 v150, v147
	v_sin_f32_e32 v151, v147
	s_cbranch_vccnz .LBB0_461
	v_mul_f32_e32 v168, v154, v163
	v_mul_f32_e32 v169, v154, v162
	v_mul_f32_e32 v166, v152, v162
	v_mul_f32_e32 v167, v152, v163
	v_fma_f32 v162, v152, v162, v168
	v_fma_f32 v163, v152, v163, v169
	v_mul_f32_e32 v162, v151, v165
	v_fma_f32 v170, v150, v164, -v162
	v_fma_f32 v171, v151, v165, -v162
	v_mov_b32_e32 v172, v151
	v_mov_b32_e32 v173, v150
	v_mul_f32_e32 v162, v150, v165
	v_fma_f32 v172, v172, v164, v162
	v_fma_f32 v173, v173, v165, v162
	v_sub_f32_e32 v162, v166, v168
	v_mov_b32_e32 v164, v170
	v_mov_b32_e32 v165, v172

; __device__ __forceinline__ unsigned cvt_pk_bf16(float lo, float hi) { const f32x2 v = {lo, hi}; const bf16x2_t b = __builtin_convertvector(v, bf16x2_t); return __builtin_bit_cast(unsigned, b); }
;     __device__ __forceinline__ void operator()(const f32x4 (&acc)[2][2][4][2], const Unit& u, int wr, int wc, int fr, int fq) const {
;     ...
;                     for (int bj = 0; bj < 2; ++bj) {
;                         u32x4 w;
; #pragma unroll
;                         for (int n = 0; n < 2; ++n) {
;                             f32x4 x = v[bj][n] * rstd * *(const f32x4*)(g + 32 * bj + 8 * fqo + 4 * n);
;                             if (latent) {
;                                 const float a0 = pos[bj] * fr0[n], a1 = pos[bj] * fr1[n];
;                                 const float c0 = __builtin_amdgcn_cosf(a0), s0 = __builtin_amdgcn_sinf(a0), c1 = __builtin_amdgcn_cosf(a1), s1 = __builtin_amdgcn_sinf(a1);
;                                 x = (f32x4){x[0] * c0 - x[1] * s0, x[1] * c0 + x[0] * s0, x[2] * c1 - x[3] * s1, x[3] * c1 + x[2] * s1};
;                             }
;                             if (n == 0) { w.x = cvt_pk_bf16(x[0], x[1]); w.y = cvt_pk_bf16(x[2], x[3]); } else { w.z = cvt_pk_bf16(x[0], x[1]); w.w = cvt_pk_bf16(x[2], x[3]); }
;                         }
;                         *(u32x4*)(dst + (size_t)row * 64 + 32 * bj + 8 * fq) = w;
.LBB0_465:
	v_ashrrev_i32_e32 v157, 31, v156
	v_lshlrev_b64 v[156:157], 7, v[156:157]
	v_cvt_pk_bf16_f32 v158, v158, v159
	v_cvt_pk_bf16_f32 v159, v160, v161
	v_lshl_add_u64 v[168:169], v[142:143], 0, v[156:157]
	v_cvt_pk_bf16_f32 v160, v170, v171
	v_cvt_pk_bf16_f32 v161, v172, v173
	global_store_dwordx4 v[168:169], v[158:161], off
	s_nop 2
	v_mov_b32_e32 v156, v120
	v_mov_b32_e32 v157, v121
	v_mov_b32_e32 v158, v122
	v_mov_b32_e32 v159, v123
	v_add_u32_e32 v141, 16, v235
	v_and_b32_e32 v141, 63, v141
	v_cvt_f32_ubyte0_e32 v141, v141
	v_mul_f32_e32 v160, v94, v166
	v_mul_f32_e32 v161, v95, v167
	v_mul_f32_e32 v166, v92, v162
	v_mul_f32_e32 v167, v93, v163
	v_mul_f32_e32 v147, v194, v141
	v_mul_f32_e32 v149, v237, v141
	s_and_b64 vcc, exec, s[36:37]
	v_mul_f32_e32 v172, v160, v158
	v_mul_f32_e32 v173, v161, v159
	v_mul_f32_e32 v170, v166, v156
	v_mul_f32_e32 v171, v167, v157
	v_cos_f32_e32 v158, v147
	v_sin_f32_e32 v160, v147
	v_cos_f32_e32 v156, v149
	v_sin_f32_e32 v157, v149
	s_cbranch_vccnz .LBB0_467
	v_mul_f32_e32 v174, v160, v171
	v_mul_f32_e32 v175, v160, v170
	v_mul_f32_e32 v166, v158, v170
	v_mul_f32_e32 v167, v158, v171
	v_fma_f32 v170, v158, v170, v174
	v_fma_f32 v171, v158, v171, v175
	v_mul_f32_e32 v170, v157, v173
	v_fma_f32 v176, v156, v172, -v170
	v_fma_f32 v177, v157, v173, -v170
	v_mov_b32_e32 v178, v157
	v_mov_b32_e32 v179, v156
	v_mul_f32_e32 v170, v156, v173
	v_fma_f32 v178, v178, v172, v170
	v_fma_f32 v179, v179, v173, v170
	v_sub_f32_e32 v170, v166, v174
	v_mov_b32_e32 v172, v176
	v_mov_b32_e32 v173, v178
.LBB0_467:
	v_mov_b32_e32 v166, v162
	v_mov_b32_e32 v167, v162
	v_mul_f32_e32 v174, v88, v162
	v_mul_f32_e32 v175, v89, v163
	v_mov_b32_e32 v162, v124
	v_mov_b32_e32 v163, v125
	v_mov_b32_e32 v164, v126
	v_mov_b32_e32 v165, v127
	v_mul_f32_e32 v166, v90, v166
	v_mul_f32_e32 v167, v91, v167
	v_mul_f32_e32 v147, v238, v141
	v_mul_f32_e32 v141, v239, v141
	s_and_b64 vcc, exec, s[36:37]
	v_mul_f32_e32 v176, v166, v164
	v_mul_f32_e32 v177, v167, v165
	v_mul_f32_e32 v174, v174, v162
	v_mul_f32_e32 v175, v175, v163
	v_cos_f32_e32 v164, v147
	v_sin_f32_e32 v166, v147
	v_cos_f32_e32 v162, v141
	v_sin_f32_e32 v163, v141
	s_cbranch_vccnz .LBB0_469
	v_mul_f32_e32 v182, v166, v175
	v_mul_f32_e32 v183, v166, v174
	v_mul_f32_e32 v178, v164, v174
	v_mul_f32_e32 v179, v164, v175
	v_fma_f32 v174, v164, v174, v182
	v_fma_f32 v175, v164, v175, v183
	v_mul_f32_e32 v174, v163, v177
	v_fma_f32 v184, v162, v176, -v174
	v_fma_f32 v185, v163, v177, -v174
	v_mov_b32_e32 v186, v163
	v_mov_b32_e32 v187, v162
	v_mul_f32_e32 v174, v162, v177
	v_fma_f32 v186, v186, v176, v174
	v_fma_f32 v187, v187, v177, v174
	v_sub_f32_e32 v174, v178, v182
	v_mov_b32_e32 v176, v184
	v_mov_b32_e32 v177, v186

; __device__ __forceinline__ unsigned cvt_pk_bf16(float lo, float hi) { const f32x2 v = {lo, hi}; const bf16x2_t b = __builtin_convertvector(v, bf16x2_t); return __builtin_bit_cast(unsigned, b); }
;     __device__ __forceinline__ void operator()(const f32x4 (&acc)[2][2][4][2], const Unit& u, int wr, int wc, int fr, int fq) const {
;     ...
;                     for (int bj = 0; bj < 2; ++bj) {
;                         u32x4 w;
; #pragma unroll
;                         for (int n = 0; n < 2; ++n) {
;                             f32x4 x = v[bj][n] * rstd * *(const f32x4*)(g + 32 * bj + 8 * fqo + 4 * n);
;                             if (latent) {
;                                 const float a0 = pos[bj] * fr0[n], a1 = pos[bj] * fr1[n];
;                                 const float c0 = __builtin_amdgcn_cosf(a0), s0 = __builtin_amdgcn_sinf(a0), c1 = __builtin_amdgcn_cosf(a1), s1 = __builtin_amdgcn_sinf(a1);
;                                 x = (f32x4){x[0] * c0 - x[1] * s0, x[1] * c0 + x[0] * s0, x[2] * c1 - x[3] * s1, x[3] * c1 + x[2] * s1};
;                             }
;                             if (n == 0) { w.x = cvt_pk_bf16(x[0], x[1]); w.y = cvt_pk_bf16(x[2], x[3]); } else { w.z = cvt_pk_bf16(x[0], x[1]); w.w = cvt_pk_bf16(x[2], x[3]); }
;                         }
;                         *(u32x4*)(dst + (size_t)row * 64 + 32 * bj + 8 * fq) = w;
.LBB0_473:
	v_ashrrev_i32_e32 v169, 31, v168
	v_lshlrev_b64 v[168:169], 7, v[168:169]
	v_cvt_pk_bf16_f32 v170, v170, v171
	v_cvt_pk_bf16_f32 v171, v172, v173
	v_xor_b32_e32 v141, 32, v180
	v_lshl_add_u64 v[180:181], v[142:143], 0, v[168:169]
	v_cvt_pk_bf16_f32 v172, v182, v183
	v_cvt_pk_bf16_f32 v173, v184, v185
	global_store_dwordx4 v[180:181], v[170:173], off
	s_nop 2
	v_mov_b32_e32 v168, v120
	v_mov_b32_e32 v169, v121
	v_mov_b32_e32 v170, v122
	v_mov_b32_e32 v171, v123
	v_cvt_f32_ubyte0_e32 v141, v141
	v_mul_f32_e32 v172, v78, v178
	v_mul_f32_e32 v173, v79, v179
	v_mul_f32_e32 v178, v76, v174
	v_mul_f32_e32 v179, v77, v175
	v_mul_f32_e32 v147, v194, v141
	v_mul_f32_e32 v149, v237, v141
	s_and_b64 vcc, exec, s[36:37]
	v_mul_f32_e32 v184, v172, v170
	v_mul_f32_e32 v185, v173, v171
	v_mul_f32_e32 v182, v178, v168
	v_mul_f32_e32 v183, v179, v169
	v_cos_f32_e32 v170, v147
	v_sin_f32_e32 v172, v147
	v_cos_f32_e32 v168, v149
	v_sin_f32_e32 v169, v149
	s_cbranch_vccnz .LBB0_475
	v_mul_f32_e32 v186, v172, v183
	v_mul_f32_e32 v187, v172, v182
	v_mul_f32_e32 v178, v170, v182
	v_mul_f32_e32 v179, v170, v183
	v_fma_f32 v182, v170, v182, v186
	v_fma_f32 v183, v170, v183, v187
	v_mul_f32_e32 v182, v169, v185
	v_fma_f32 v188, v168, v184, -v182
	v_fma_f32 v189, v169, v185, -v182
	v_mov_b32_e32 v190, v169
	v_mov_b32_e32 v191, v168
	v_mul_f32_e32 v182, v168, v185
	v_fma_f32 v190, v190, v184, v182
	v_fma_f32 v191, v191, v185, v182
	v_sub_f32_e32 v182, v178, v186
	v_mov_b32_e32 v184, v188
	v_mov_b32_e32 v185, v190
.LBB0_475:
	v_mov_b32_e32 v178, v174
	v_mov_b32_e32 v179, v174
	v_mul_f32_e32 v186, v72, v174
	v_mul_f32_e32 v187, v73, v175
	v_mov_b32_e32 v174, v124
	v_mov_b32_e32 v175, v125
	v_mov_b32_e32 v176, v126
	v_mov_b32_e32 v177, v127
	v_mul_f32_e32 v178, v74, v178
	v_mul_f32_e32 v179, v75, v179
	v_mul_f32_e32 v147, v238, v141
	v_mul_f32_e32 v141, v239, v141
	s_and_b64 vcc, exec, s[36:37]
	v_mul_f32_e32 v188, v178, v176
	v_mul_f32_e32 v189, v179, v177
	v_mul_f32_e32 v186, v186, v174
	v_mul_f32_e32 v187, v187, v175
	v_cos_f32_e32 v176, v147
	v_sin_f32_e32 v178, v147
	v_cos_f32_e32 v174, v141
	v_sin_f32_e32 v175, v141
	s_cbranch_vccnz .LBB0_477
	v_mul_f32_e32 v208, v178, v187
	v_mul_f32_e32 v209, v178, v186
	v_mul_f32_e32 v190, v176, v186
	v_mul_f32_e32 v191, v176, v187
	v_fma_f32 v186, v176, v186, v208
	v_fma_f32 v187, v176, v187, v209
	v_mul_f32_e32 v186, v175, v189
	v_fma_f32 v210, v174, v188, -v186
	v_fma_f32 v211, v175, v189, -v186
	v_mov_b32_e32 v212, v175
	v_mov_b32_e32 v213, v174
	v_mul_f32_e32 v186, v174, v189
	v_fma_f32 v212, v212, v188, v186
	v_fma_f32 v213, v213, v189, v186
	v_sub_f32_e32 v186, v190, v208
	v_mov_b32_e32 v188, v210
	v_mov_b32_e32 v189, v212

; __device__ __forceinline__ unsigned cvt_pk_bf16(float lo, float hi) { const f32x2 v = {lo, hi}; const bf16x2_t b = __builtin_convertvector(v, bf16x2_t); return __builtin_bit_cast(unsigned, b); }
;     __device__ __forceinline__ void operator()(const f32x4 (&acc)[2][2][4][2], const Unit& u, int wr, int wc, int fr, int fq) const {
;     ...
;                     for (int bj = 0; bj < 2; ++bj) {
;                         u32x4 w;
; #pragma unroll
;                         for (int n = 0; n < 2; ++n) {
;                             f32x4 x = v[bj][n] * rstd * *(const f32x4*)(g + 32 * bj + 8 * fqo + 4 * n);
;                             if (latent) {
;                                 const float a0 = pos[bj] * fr0[n], a1 = pos[bj] * fr1[n];
;                                 const float c0 = __builtin_amdgcn_cosf(a0), s0 = __builtin_amdgcn_sinf(a0), c1 = __builtin_amdgcn_cosf(a1), s1 = __builtin_amdgcn_sinf(a1);
;                                 x = (f32x4){x[0] * c0 - x[1] * s0, x[1] * c0 + x[0] * s0, x[2] * c1 - x[3] * s1, x[3] * c1 + x[2] * s1};
;                             }
;                             if (n == 0) { w.x = cvt_pk_bf16(x[0], x[1]); w.y = cvt_pk_bf16(x[2], x[3]); } else { w.z = cvt_pk_bf16(x[0], x[1]); w.w = cvt_pk_bf16(x[2], x[3]); }
;                         }
;                         *(u32x4*)(dst + (size_t)row * 64 + 32 * bj + 8 * fq) = w;
.LBB0_481:
	v_ashrrev_i32_e32 v181, 31, v180
	v_lshlrev_b64 v[180:181], 7, v[180:181]
	v_cvt_pk_bf16_f32 v182, v182, v183
	v_cvt_pk_bf16_f32 v183, v184, v185
	v_lshl_add_u64 v[208:209], v[142:143], 0, v[180:181]
	v_cvt_pk_bf16_f32 v184, v210, v211
	v_cvt_pk_bf16_f32 v185, v212, v213
	global_store_dwordx4 v[208:209], v[182:185], off
	s_nop 2
	v_mov_b32_e32 v180, v120
	v_mov_b32_e32 v181, v121
	v_mov_b32_e32 v182, v122
	v_mov_b32_e32 v183, v123
	v_add_u32_e32 v141, 48, v235
	v_and_b32_e32 v141, 63, v141
	v_cvt_f32_ubyte0_e32 v141, v141
	v_mul_f32_e32 v184, v70, v190
	v_mul_f32_e32 v185, v71, v191
	v_mul_f32_e32 v190, v68, v186
	v_mul_f32_e32 v191, v69, v187
	v_mul_f32_e32 v147, v194, v141
	v_mul_f32_e32 v149, v237, v141
	s_and_b64 vcc, exec, s[36:37]
	v_mul_f32_e32 v212, v184, v182
	v_mul_f32_e32 v213, v185, v183
	v_mul_f32_e32 v210, v190, v180
	v_mul_f32_e32 v211, v191, v181
	v_cos_f32_e32 v182, v147
	v_sin_f32_e32 v184, v147
	v_cos_f32_e32 v180, v149
	v_sin_f32_e32 v181, v149
	s_cbranch_vccnz .LBB0_483
	v_mul_f32_e32 v214, v184, v211
	v_mul_f32_e32 v215, v184, v210
	v_mul_f32_e32 v190, v182, v210
	v_mul_f32_e32 v191, v182, v211
	v_fma_f32 v210, v182, v210, v214
	v_fma_f32 v211, v182, v211, v215
	v_mul_f32_e32 v210, v181, v213
	v_fma_f32 v216, v180, v212, -v210
	v_fma_f32 v217, v181, v213, -v210
	v_mov_b32_e32 v218, v181
	v_mov_b32_e32 v219, v180
	v_mul_f32_e32 v210, v180, v213
	v_fma_f32 v218, v218, v212, v210
	v_fma_f32 v219, v219, v213, v210
	v_sub_f32_e32 v210, v190, v214
	v_mov_b32_e32 v212, v216
	v_mov_b32_e32 v213, v218
.LBB0_483:
	v_mov_b32_e32 v190, v186
	v_mov_b32_e32 v191, v186
	v_mul_f32_e32 v214, v64, v186
	v_mul_f32_e32 v215, v65, v187
	v_mov_b32_e32 v186, v124
	v_mov_b32_e32 v187, v125
	v_mov_b32_e32 v188, v126
	v_mov_b32_e32 v189, v127
	v_mul_f32_e32 v190, v66, v190
	v_mul_f32_e32 v191, v67, v191
	v_mul_f32_e32 v147, v238, v141
	v_mul_f32_e32 v141, v239, v141
	s_and_b64 vcc, exec, s[36:37]
	v_mul_f32_e32 v216, v190, v188
	v_mul_f32_e32 v217, v191, v189
	v_mul_f32_e32 v214, v214, v186
	v_mul_f32_e32 v215, v215, v187
	v_cos_f32_e32 v188, v147
	v_sin_f32_e32 v190, v147
	v_cos_f32_e32 v186, v141
	v_sin_f32_e32 v187, v141
	s_cbranch_vccnz .LBB0_485
	v_mul_f32_e32 v220, v190, v215
	v_mul_f32_e32 v221, v190, v214
	v_mul_f32_e32 v218, v188, v214
	v_mul_f32_e32 v219, v188, v215
	v_fma_f32 v214, v188, v214, v220
	v_fma_f32 v215, v188, v215, v221
	v_mul_f32_e32 v214, v187, v217
	v_fma_f32 v222, v186, v216, -v214
	v_fma_f32 v223, v187, v217, -v214
	v_mov_b32_e32 v226, v187
	v_mov_b32_e32 v227, v186
	v_mul_f32_e32 v214, v186, v217
	v_fma_f32 v226, v226, v216, v214
	v_fma_f32 v227, v227, v217, v214
	v_sub_f32_e32 v214, v218, v220
	v_mov_b32_e32 v216, v222
	v_mov_b32_e32 v217, v226

; __device__ __forceinline__ unsigned cvt_pk_bf16(float lo, float hi) { const f32x2 v = {lo, hi}; const bf16x2_t b = __builtin_convertvector(v, bf16x2_t); return __builtin_bit_cast(unsigned, b); }
;     __device__ __forceinline__ void operator()(const f32x4 (&acc)[2][2][4][2], const Unit& u, int wr, int wc, int fr, int fq) const {
;     ...
;                     for (int bj = 0; bj < 2; ++bj) {
;                         u32x4 w;
; #pragma unroll
;                         for (int n = 0; n < 2; ++n) {
;                             f32x4 x = v[bj][n] * rstd * *(const f32x4*)(g + 32 * bj + 8 * fqo + 4 * n);
;                             if (latent) {
;                                 const float a0 = pos[bj] * fr0[n], a1 = pos[bj] * fr1[n];
;                                 const float c0 = __builtin_amdgcn_cosf(a0), s0 = __builtin_amdgcn_sinf(a0), c1 = __builtin_amdgcn_cosf(a1), s1 = __builtin_amdgcn_sinf(a1);
;                                 x = (f32x4){x[0] * c0 - x[1] * s0, x[1] * c0 + x[0] * s0, x[2] * c1 - x[3] * s1, x[3] * c1 + x[2] * s1};
;                             }
;                             if (n == 0) { w.x = cvt_pk_bf16(x[0], x[1]); w.y = cvt_pk_bf16(x[2], x[3]); } else { w.z = cvt_pk_bf16(x[0], x[1]); w.w = cvt_pk_bf16(x[2], x[3]); }
;                         }
;                         *(u32x4*)(dst + (size_t)row * 64 + 32 * bj + 8 * fq) = w;
.LBB0_489:
	v_ashrrev_i32_e32 v211, 31, v210
	v_lshlrev_b64 v[210:211], 7, v[210:211]
	v_cvt_pk_bf16_f32 v214, v214, v215
	v_cvt_pk_bf16_f32 v215, v216, v217
	v_lshl_add_u64 v[210:211], v[142:143], 0, v[210:211]
	v_cvt_pk_bf16_f32 v216, v220, v221
	v_cvt_pk_bf16_f32 v217, v222, v223
	global_store_dwordx4 v[210:211], v[214:217], off
	s_nop 2
	v_mov_b32_e32 v214, v120
	v_mov_b32_e32 v215, v121
	v_mov_b32_e32 v216, v122
	v_mov_b32_e32 v217, v123
	v_mul_f32_e32 v218, v46, v218
	v_mul_f32_e32 v219, v47, v219
	v_mul_f32_e32 v220, v44, v208
	v_mul_f32_e32 v221, v45, v209
	s_and_b64 vcc, exec, s[36:37]
	v_mul_f32_e32 v216, v218, v216
	v_mul_f32_e32 v217, v219, v217
	v_mul_f32_e32 v214, v220, v214
	v_mul_f32_e32 v215, v221, v215
	s_cbranch_vccnz .LBB0_491
	v_mul_f32_e32 v149, v148, v214
	v_mul_f32_e32 v148, v148, v215
	v_mul_f32_e32 v218, v146, v214
	v_mul_f32_e32 v219, v146, v215
	v_fma_f32 v214, v146, v214, v148
	v_fma_f32 v215, v146, v215, v149
	v_mul_f32_e32 v146, v145, v217
	v_fma_f32 v147, v145, v217, -v146
	v_fma_f32 v146, v144, v216, -v146
	v_mov_b32_e32 v220, v145
	v_mov_b32_e32 v221, v144
	v_mul_f32_e32 v144, v144, v217
	v_fma_f32 v145, v221, v217, v144
	v_fma_f32 v144, v220, v216, v144
	v_sub_f32_e32 v214, v218, v148
	v_mov_b32_e32 v216, v146
	v_mov_b32_e32 v217, v144
.LBB0_491:
	v_mov_b32_e32 v144, v124
	v_mov_b32_e32 v145, v125
	v_mov_b32_e32 v146, v126
	v_mov_b32_e32 v147, v127
	v_mov_b32_e32 v148, v208
	v_mov_b32_e32 v149, v208
	v_mul_f32_e32 v208, v40, v208
	v_mul_f32_e32 v209, v41, v209
	v_mul_f32_e32 v148, v42, v148
	v_mul_f32_e32 v149, v43, v149
	s_and_b64 vcc, exec, s[36:37]
	v_mul_f32_e32 v146, v148, v146
	v_mul_f32_e32 v147, v149, v147
	v_mul_f32_e32 v144, v208, v144
	v_mul_f32_e32 v145, v209, v145
	s_cbranch_vccnz .LBB0_493
	v_mul_f32_e32 v155, v154, v144
	v_mul_f32_e32 v154, v154, v145
	v_mul_f32_e32 v148, v152, v144
	v_mul_f32_e32 v149, v152, v145
	v_fma_f32 v144, v152, v144, v154
	v_fma_f32 v145, v152, v145, v155
	v_mul_f32_e32 v144, v151, v147
	v_fma_f32 v152, v150, v146, -v144
	v_fma_f32 v153, v151, v147, -v144
	v_mov_b32_e32 v208, v151
	v_mov_b32_e32 v209, v150
	v_mul_f32_e32 v144, v150, v147
	v_fma_f32 v150, v208, v146, v144
	v_fma_f32 v151, v209, v147, v144
	v_sub_f32_e32 v144, v148, v154
	v_mov_b32_e32 v146, v152
	v_mov_b32_e32 v147, v150

; __device__ __forceinline__ unsigned cvt_pk_bf16(float lo, float hi) { const f32x2 v = {lo, hi}; const bf16x2_t b = __builtin_convertvector(v, bf16x2_t); return __builtin_bit_cast(unsigned, b); }
;     __device__ __forceinline__ void operator()(const f32x4 (&acc)[2][2][4][2], const Unit& u, int wr, int wc, int fr, int fq) const {
;     ...
;                     for (int bj = 0; bj < 2; ++bj) {
;                         u32x4 w;
; #pragma unroll
;                         for (int n = 0; n < 2; ++n) {
;                             f32x4 x = v[bj][n] * rstd * *(const f32x4*)(g + 32 * bj + 8 * fqo + 4 * n);
;                             if (latent) {
;                                 const float a0 = pos[bj] * fr0[n], a1 = pos[bj] * fr1[n];
;                                 const float c0 = __builtin_amdgcn_cosf(a0), s0 = __builtin_amdgcn_sinf(a0), c1 = __builtin_amdgcn_cosf(a1), s1 = __builtin_amdgcn_sinf(a1);
;                                 x = (f32x4){x[0] * c0 - x[1] * s0, x[1] * c0 + x[0] * s0, x[2] * c1 - x[3] * s1, x[3] * c1 + x[2] * s1};
;                             }
;                             if (n == 0) { w.x = cvt_pk_bf16(x[0], x[1]); w.y = cvt_pk_bf16(x[2], x[3]); } else { w.z = cvt_pk_bf16(x[0], x[1]); w.w = cvt_pk_bf16(x[2], x[3]); }
;                         }
;                         *(u32x4*)(dst + (size_t)row * 64 + 32 * bj + 8 * fq) = w;
.LBB0_497:
	v_ashrrev_i32_e32 v147, 31, v146
	v_lshlrev_b64 v[146:147], 7, v[146:147]
	v_cvt_pk_bf16_f32 v150, v150, v151
	v_cvt_pk_bf16_f32 v151, v152, v153
	v_lshl_add_u64 v[146:147], v[142:143], 0, v[146:147]
	v_cvt_pk_bf16_f32 v152, v208, v209
	v_cvt_pk_bf16_f32 v153, v210, v211
	global_store_dwordx4 v[146:147], v[150:153], off
	s_nop 2
	v_mov_b32_e32 v150, v120
	v_mov_b32_e32 v151, v121
	v_mov_b32_e32 v152, v122
	v_mov_b32_e32 v153, v123
	v_mul_f32_e32 v154, v30, v154
	v_mul_f32_e32 v155, v31, v155
	v_mul_f32_e32 v208, v28, v144
	v_mul_f32_e32 v209, v29, v145
	s_and_b64 vcc, exec, s[36:37]
	v_mul_f32_e32 v152, v154, v152
	v_mul_f32_e32 v153, v155, v153
	v_mul_f32_e32 v150, v208, v150
	v_mul_f32_e32 v151, v209, v151
	s_cbranch_vccnz .LBB0_499
	v_mul_f32_e32 v161, v160, v150
	v_mul_f32_e32 v160, v160, v151
	v_mul_f32_e32 v154, v158, v150
	v_mul_f32_e32 v155, v158, v151
	v_fma_f32 v150, v158, v150, v160
	v_fma_f32 v151, v158, v151, v161
	v_mul_f32_e32 v150, v157, v153
	v_fma_f32 v158, v156, v152, -v150
	v_fma_f32 v159, v157, v153, -v150
	v_mov_b32_e32 v208, v157
	v_mov_b32_e32 v209, v156
	v_mul_f32_e32 v150, v156, v153
	v_fma_f32 v156, v208, v152, v150
	v_fma_f32 v157, v209, v153, v150
	v_sub_f32_e32 v150, v154, v160
	v_mov_b32_e32 v152, v158
	v_mov_b32_e32 v153, v156
.LBB0_499:
	v_mov_b32_e32 v154, v124
	v_mov_b32_e32 v155, v125
	v_mov_b32_e32 v156, v126
	v_mov_b32_e32 v157, v127
	v_mov_b32_e32 v148, v144
	v_mov_b32_e32 v149, v144
	v_mul_f32_e32 v144, v24, v144
	v_mul_f32_e32 v145, v25, v145
	v_mul_f32_e32 v148, v26, v148
	v_mul_f32_e32 v149, v27, v149
	s_and_b64 vcc, exec, s[36:37]
	v_mul_f32_e32 v148, v148, v156
	v_mul_f32_e32 v149, v149, v157
	v_mul_f32_e32 v144, v144, v154
	v_mul_f32_e32 v145, v145, v155
	s_cbranch_vccnz .LBB0_501
	v_mul_f32_e32 v156, v166, v145
	v_mul_f32_e32 v157, v166, v144
	v_mul_f32_e32 v154, v164, v144
	v_mul_f32_e32 v155, v164, v145
	v_fma_f32 v144, v164, v144, v156
	v_fma_f32 v145, v164, v145, v157
	v_mul_f32_e32 v144, v163, v149
	v_fma_f32 v158, v162, v148, -v144
	v_fma_f32 v159, v163, v149, -v144
	v_mov_b32_e32 v160, v163
	v_mov_b32_e32 v161, v162
	v_mul_f32_e32 v144, v162, v149
	v_fma_f32 v160, v160, v148, v144
	v_fma_f32 v161, v161, v149, v144
	v_sub_f32_e32 v144, v154, v156
	v_mov_b32_e32 v148, v158
	v_mov_b32_e32 v149, v160

; __device__ __forceinline__ unsigned cvt_pk_bf16(float lo, float hi) { const f32x2 v = {lo, hi}; const bf16x2_t b = __builtin_convertvector(v, bf16x2_t); return __builtin_bit_cast(unsigned, b); }
;     __device__ __forceinline__ void operator()(const f32x4 (&acc)[2][2][4][2], const Unit& u, int wr, int wc, int fr, int fq) const {
;     ...
;                     for (int bj = 0; bj < 2; ++bj) {
;                         u32x4 w;
; #pragma unroll
;                         for (int n = 0; n < 2; ++n) {
;                             f32x4 x = v[bj][n] * rstd * *(const f32x4*)(g + 32 * bj + 8 * fqo + 4 * n);
;                             if (latent) {
;                                 const float a0 = pos[bj] * fr0[n], a1 = pos[bj] * fr1[n];
;                                 const float c0 = __builtin_amdgcn_cosf(a0), s0 = __builtin_amdgcn_sinf(a0), c1 = __builtin_amdgcn_cosf(a1), s1 = __builtin_amdgcn_sinf(a1);
;                                 x = (f32x4){x[0] * c0 - x[1] * s0, x[1] * c0 + x[0] * s0, x[2] * c1 - x[3] * s1, x[3] * c1 + x[2] * s1};
;                             }
;                             if (n == 0) { w.x = cvt_pk_bf16(x[0], x[1]); w.y = cvt_pk_bf16(x[2], x[3]); } else { w.z = cvt_pk_bf16(x[0], x[1]); w.w = cvt_pk_bf16(x[2], x[3]); }
;                         }
;                         *(u32x4*)(dst + (size_t)row * 64 + 32 * bj + 8 * fq) = w;
.LBB0_505:
	v_ashrrev_i32_e32 v147, 31, v146
	v_lshlrev_b64 v[146:147], 7, v[146:147]
	v_cvt_pk_bf16_f32 v150, v150, v151
	v_cvt_pk_bf16_f32 v151, v152, v153
	v_lshl_add_u64 v[146:147], v[142:143], 0, v[146:147]
	v_cvt_pk_bf16_f32 v152, v156, v157
	v_cvt_pk_bf16_f32 v153, v158, v159
	global_store_dwordx4 v[146:147], v[150:153], off
	s_nop 2
	v_mov_b32_e32 v150, v120
	v_mov_b32_e32 v151, v121
	v_mov_b32_e32 v152, v122
	v_mov_b32_e32 v153, v123
	v_mul_f32_e32 v154, v14, v154
	v_mul_f32_e32 v155, v15, v155
	v_mul_f32_e32 v156, v12, v144
	v_mul_f32_e32 v157, v13, v145
	s_and_b64 vcc, exec, s[36:37]
	v_mul_f32_e32 v152, v154, v152
	v_mul_f32_e32 v153, v155, v153
	v_mul_f32_e32 v150, v156, v150
	v_mul_f32_e32 v151, v157, v151
	s_cbranch_vccnz .LBB0_507
	v_mul_f32_e32 v156, v172, v151
	v_mul_f32_e32 v157, v172, v150
	v_mul_f32_e32 v154, v170, v150
	v_mul_f32_e32 v155, v170, v151
	v_fma_f32 v150, v170, v150, v156
	v_fma_f32 v151, v170, v151, v157
	v_mul_f32_e32 v150, v169, v153
	v_fma_f32 v158, v168, v152, -v150
	v_fma_f32 v159, v169, v153, -v150
	v_mov_b32_e32 v160, v169
	v_mov_b32_e32 v161, v168
	v_mul_f32_e32 v150, v168, v153
	v_fma_f32 v160, v160, v152, v150
	v_fma_f32 v161, v161, v153, v150
	v_sub_f32_e32 v150, v154, v156
	v_mov_b32_e32 v152, v158
	v_mov_b32_e32 v153, v160
.LBB0_507:
	v_mov_b32_e32 v154, v124
	v_mov_b32_e32 v155, v125
	v_mov_b32_e32 v156, v126
	v_mov_b32_e32 v157, v127
	v_mov_b32_e32 v148, v144
	v_mov_b32_e32 v149, v144
	v_mul_f32_e32 v144, v8, v144
	v_mul_f32_e32 v145, v9, v145
	v_mul_f32_e32 v148, v10, v148
	v_mul_f32_e32 v149, v11, v149
	s_and_b64 vcc, exec, s[36:37]
	v_mul_f32_e32 v148, v148, v156
	v_mul_f32_e32 v149, v149, v157
	v_mul_f32_e32 v144, v144, v154
	v_mul_f32_e32 v145, v145, v155
	s_cbranch_vccnz .LBB0_509
	v_mul_f32_e32 v156, v178, v145
	v_mul_f32_e32 v157, v178, v144
	v_mul_f32_e32 v154, v176, v144
	v_mul_f32_e32 v155, v176, v145
	v_fma_f32 v144, v176, v144, v156
	v_fma_f32 v145, v176, v145, v157
	v_mul_f32_e32 v144, v175, v149
	v_fma_f32 v158, v174, v148, -v144
	v_fma_f32 v159, v175, v149, -v144
	v_mov_b32_e32 v160, v175
	v_mov_b32_e32 v161, v174
	v_mul_f32_e32 v144, v174, v149
	v_fma_f32 v160, v160, v148, v144
	v_fma_f32 v161, v161, v149, v144
	v_sub_f32_e32 v144, v154, v156
	v_mov_b32_e32 v148, v158
	v_mov_b32_e32 v149, v160

; __device__ __forceinline__ unsigned cvt_pk_bf16(float lo, float hi) { const f32x2 v = {lo, hi}; const bf16x2_t b = __builtin_convertvector(v, bf16x2_t); return __builtin_bit_cast(unsigned, b); }
;     __device__ __forceinline__ void operator()(const f32x4 (&acc)[2][2][4][2], const Unit& u, int wr, int wc, int fr, int fq) const {
;     ...
;                     for (int bj = 0; bj < 2; ++bj) {
;                         u32x4 w;
; #pragma unroll
;                         for (int n = 0; n < 2; ++n) {
;                             f32x4 x = v[bj][n] * rstd * *(const f32x4*)(g + 32 * bj + 8 * fqo + 4 * n);
;                             if (latent) {
;                                 const float a0 = pos[bj] * fr0[n], a1 = pos[bj] * fr1[n];
;                                 const float c0 = __builtin_amdgcn_cosf(a0), s0 = __builtin_amdgcn_sinf(a0), c1 = __builtin_amdgcn_cosf(a1), s1 = __builtin_amdgcn_sinf(a1);
;                                 x = (f32x4){x[0] * c0 - x[1] * s0, x[1] * c0 + x[0] * s0, x[2] * c1 - x[3] * s1, x[3] * c1 + x[2] * s1};
;                             }
;                             if (n == 0) { w.x = cvt_pk_bf16(x[0], x[1]); w.y = cvt_pk_bf16(x[2], x[3]); } else { w.z = cvt_pk_bf16(x[0], x[1]); w.w = cvt_pk_bf16(x[2], x[3]); }
;                         }
;                         *(u32x4*)(dst + (size_t)row * 64 + 32 * bj + 8 * fq) = w;
.LBB0_513:
	v_ashrrev_i32_e32 v145, 31, v144
	v_lshlrev_b64 v[144:145], 7, v[144:145]
	v_cvt_pk_bf16_f32 v148, v148, v149
	v_cvt_pk_bf16_f32 v149, v150, v151
	v_lshl_add_u64 v[142:143], v[142:143], 0, v[144:145]
	v_cvt_pk_bf16_f32 v150, v154, v155
	v_cvt_pk_bf16_f32 v151, v156, v157
	global_store_dwordx4 v[142:143], v[148:151], off
	s_nop 2
	v_mov_b32_e32 v154, v120
	v_mov_b32_e32 v155, v121
	v_mov_b32_e32 v156, v122
	v_mov_b32_e32 v157, v123
	v_mul_f32_e32 v144, v6, v152
	v_mul_f32_e32 v145, v7, v153
	v_mul_f32_e32 v150, v4, v140
	v_mul_f32_e32 v151, v5, v141
	s_and_b64 vcc, exec, s[36:37]
	v_mul_f32_e32 v148, v144, v156
	v_mul_f32_e32 v149, v145, v157
	v_mul_f32_e32 v144, v150, v154
	v_mul_f32_e32 v145, v151, v155
	s_cbranch_vccnz .LBB0_515
	v_mul_f32_e32 v152, v184, v145
	v_mul_f32_e32 v153, v184, v144
	v_mul_f32_e32 v150, v182, v144
	v_mul_f32_e32 v151, v182, v145
	v_fma_f32 v144, v182, v144, v152
	v_fma_f32 v145, v182, v145, v153
	v_mul_f32_e32 v144, v181, v149
	v_fma_f32 v154, v180, v148, -v144
	v_fma_f32 v155, v181, v149, -v144
	v_mov_b32_e32 v156, v181
	v_mov_b32_e32 v157, v180
	v_mul_f32_e32 v144, v180, v149
	v_fma_f32 v156, v156, v148, v144
	v_fma_f32 v157, v157, v149, v144
	v_sub_f32_e32 v144, v150, v152
	v_mov_b32_e32 v148, v154
	v_mov_b32_e32 v149, v156
.LBB0_515:
	v_mov_b32_e32 v150, v124
	v_mov_b32_e32 v151, v125
	v_mov_b32_e32 v152, v126
	v_mov_b32_e32 v153, v127
	v_mov_b32_e32 v146, v140
	v_mov_b32_e32 v147, v140
	v_mul_f32_e32 v140, v0, v140
	v_mul_f32_e32 v141, v1, v141
	v_mul_f32_e32 v146, v2, v146
	v_mul_f32_e32 v147, v3, v147
	s_and_b64 vcc, exec, s[36:37]
	v_mul_f32_e32 v146, v146, v152
	v_mul_f32_e32 v147, v147, v153
	v_mul_f32_e32 v140, v140, v150
	v_mul_f32_e32 v141, v141, v151
	s_cbranch_vccnz .LBB0_517
	v_mul_f32_e32 v152, v190, v141
	v_mul_f32_e32 v153, v190, v140
	v_mul_f32_e32 v150, v188, v140
	v_mul_f32_e32 v151, v188, v141
	v_fma_f32 v140, v188, v140, v152
	v_fma_f32 v141, v188, v141, v153
	v_mul_f32_e32 v140, v187, v147
	v_fma_f32 v154, v186, v146, -v140
	v_fma_f32 v155, v187, v147, -v140
	v_mov_b32_e32 v156, v187
	v_mov_b32_e32 v157, v186
	v_mul_f32_e32 v140, v186, v147
	v_fma_f32 v156, v156, v146, v140
	v_fma_f32 v157, v157, v147, v140
	v_sub_f32_e32 v140, v150, v152
	v_mov_b32_e32 v146, v154
	v_mov_b32_e32 v147, v156
